# P2d: first carry-in prefix batch issued ahead of the 32 streaming loads (its L2-hot entries no longer queue behind HBM latency)
# baseline (speedup 1.0000x reference)
; __device__ __forceinline__ float bf_lo(unsigned w) { return __uint_as_float(w << 16); }
; __device__ __forceinline__ float bf_hi(unsigned w) { return __uint_as_float(w & 0xffff0000u); }
; __global__ void __launch_bounds__(NTHR, 2) hybrid_block_fwd(Args a) {
;     ...
;         f32x2 H = (f32x2){0.f, 0.f};
; #pragma unroll 4
;         for (int j = 0; j < chunk; ++j) { const f32x2 P = ((const f32x2*)(AGGP + (size_t)(b * NCH + j) * LW))[c2], Hj = ((const f32x2*)(AGGH + (size_t)(b * NCH + j) * LW))[c2]; H = P * H + Hj; }
;         const size_t r0 = (size_t)b * SEQ + (size_t)chunk * CH_L;
;         const u32x2* pab = (const u32x2*)((const unsigned*)AF + r0 * LW) + c2;
;         const unsigned* pg = (const unsigned*)(GELU_U + r0 * LW) + c2; unsigned* po = (unsigned*)(YCAT + r0 * KC + PW) + c2;
; #pragma unroll 16
;         for (int i = 0; i < CH_L; ++i) {
;             const u32x2 q = pab[(size_t)i * (LW / 2)]; const f32x2 av = (f32x2){__builtin_amdgcn_exp2f(bf_lo(q.x)), __builtin_amdgcn_exp2f(bf_lo(q.y))}, bv = (f32x2){bf_hi(q.x), bf_hi(q.y)}; const unsigned gq = pg[(size_t)i * (LW / 2)];
.LBB0_613:
	s_or_b64 exec, exec, s[0:1]
	s_waitcnt lgkmcnt(0)
	v_mov_b32_e32 v0, v212
	v_readlane_b32 s0, v248, 8
	s_barrier
	v_readlane_b32 s8, v248, 8
	s_nop 3
	s_nop 1
	v_add_u32_e32 v1, s8, v0
	v_and_b32_e32 v1, 0x3ff, v1
	v_lshlrev_b32_e32 v2, 3, v1
	v_lshlrev_b32_e32 v3, 2, v1
	v_add_u32_e32 v6, 0x100000, v2
	s_lshr_b32 s9, s8, 10
	s_and_b32 s10, s9, 63
	s_lshr_b32 s11, s9, 6
	s_lshl_b32 s21, s9, 20
	s_add_u32 s12, s92, s21
	s_addc_u32 s13, s93, 0
	s_lshl_b32 s21, s9, 19
	s_add_u32 s14, s94, s21
	s_addc_u32 s15, s95, 0
	s_add_u32 s14, s14, 0x9f00000
	s_addc_u32 s15, s15, 0
	s_mul_i32 s21, s9, 0xc0000
	s_add_u32 s18, s94, s21
	s_addc_u32 s19, s95, 0
	s_add_u32 s18, s18, 0x15f00800
	s_addc_u32 s19, s19, 0
	s_lshl_b32 s21, s11, 19
	s_add_u32 s0, s94, s21
	s_addc_u32 s1, s95, 0
	s_add_u32 s0, s0, 0x100000
	s_addc_u32 s1, s1, 0
	v_mov_b32_e32 v4, 0
	v_mov_b32_e32 v5, 0
	s_cmp_eq_u32 s10, 0
	s_cbranch_scc1 .Lp2d_main_only
	global_load_dwordx2 v[100:101], v2, s[0:1]
	global_load_dwordx2 v[102:103], v6, s[0:1]
	s_add_u32 s0, s0, 0x2000
	s_addc_u32 s1, s1, 0
	global_load_dwordx2 v[104:105], v2, s[0:1]
	global_load_dwordx2 v[106:107], v6, s[0:1]
	s_add_u32 s0, s0, 0x2000
	s_addc_u32 s1, s1, 0
	global_load_dwordx2 v[108:109], v2, s[0:1]
	global_load_dwordx2 v[110:111], v6, s[0:1]
	s_add_u32 s0, s0, 0x2000
	s_addc_u32 s1, s1, 0
	global_load_dwordx2 v[112:113], v2, s[0:1]
	global_load_dwordx2 v[114:115], v6, s[0:1]
	s_add_u32 s0, s0, 0x2000
	s_addc_u32 s1, s1, 0
	global_load_dwordx2 v[116:117], v2, s[0:1]
	global_load_dwordx2 v[118:119], v6, s[0:1]
	s_add_u32 s0, s0, 0x2000
	s_addc_u32 s1, s1, 0
	global_load_dwordx2 v[120:121], v2, s[0:1]
	global_load_dwordx2 v[122:123], v6, s[0:1]
	s_add_u32 s0, s0, 0x2000
	s_addc_u32 s1, s1, 0
	global_load_dwordx2 v[124:125], v2, s[0:1]
	global_load_dwordx2 v[126:127], v6, s[0:1]
	s_add_u32 s0, s0, 0x2000
	s_addc_u32 s1, s1, 0
	global_load_dwordx2 v[128:129], v2, s[0:1]
	global_load_dwordx2 v[130:131], v6, s[0:1]
	s_add_u32 s0, s0, 0x2000
	s_addc_u32 s1, s1, 0
	global_load_dwordx2 v[132:133], v2, s[0:1]
	global_load_dwordx2 v[134:135], v6, s[0:1]
	s_add_u32 s0, s0, 0x2000
	s_addc_u32 s1, s1, 0
	global_load_dwordx2 v[136:137], v2, s[0:1]
	global_load_dwordx2 v[138:139], v6, s[0:1]
	s_add_u32 s0, s0, 0x2000
	s_addc_u32 s1, s1, 0
	global_load_dwordx2 v[140:141], v2, s[0:1]
	global_load_dwordx2 v[142:143], v6, s[0:1]
	s_add_u32 s0, s0, 0x2000
	s_addc_u32 s1, s1, 0
	global_load_dwordx2 v[144:145], v2, s[0:1]
	global_load_dwordx2 v[146:147], v6, s[0:1]
	s_add_u32 s0, s0, 0x2000
	s_addc_u32 s1, s1, 0
	global_load_dwordx2 v[148:149], v2, s[0:1]
	global_load_dwordx2 v[150:151], v6, s[0:1]
	s_add_u32 s0, s0, 0x2000
	s_addc_u32 s1, s1, 0
	global_load_dwordx2 v[152:153], v2, s[0:1]
	global_load_dwordx2 v[154:155], v6, s[0:1]
	s_add_u32 s0, s0, 0x2000
	s_addc_u32 s1, s1, 0
	global_load_dwordx2 v[156:157], v2, s[0:1]
	global_load_dwordx2 v[158:159], v6, s[0:1]
	s_add_u32 s0, s0, 0x2000
	s_addc_u32 s1, s1, 0
	global_load_dwordx2 v[160:161], v2, s[0:1]
	global_load_dwordx2 v[162:163], v6, s[0:1]
	s_add_u32 s0, s0, 0x2000
	s_addc_u32 s1, s1, 0
	global_load_dwordx2 v[32:33], v2, s[12:13] nt
	global_load_dword v64, v3, s[14:15] nt
	s_add_u32 s12, s12, 0x2000
	s_addc_u32 s13, s13, 0
	s_add_u32 s14, s14, 0x1000
	s_addc_u32 s15, s15, 0
	global_load_dwordx2 v[34:35], v2, s[12:13] nt
	global_load_dword v65, v3, s[14:15] nt
	s_add_u32 s12, s12, 0x2000
	s_addc_u32 s13, s13, 0
	s_add_u32 s14, s14, 0x1000
	s_addc_u32 s15, s15, 0
	global_load_dwordx2 v[36:37], v2, s[12:13] nt
	global_load_dword v66, v3, s[14:15] nt
	s_add_u32 s12, s12, 0x2000
	s_addc_u32 s13, s13, 0
	s_add_u32 s14, s14, 0x1000
	s_addc_u32 s15, s15, 0
	global_load_dwordx2 v[38:39], v2, s[12:13] nt
	global_load_dword v67, v3, s[14:15] nt
	s_add_u32 s12, s12, 0x2000
	s_addc_u32 s13, s13, 0
	s_add_u32 s14, s14, 0x1000
	s_addc_u32 s15, s15, 0
	global_load_dwordx2 v[40:41], v2, s[12:13] nt
	global_load_dword v68, v3, s[14:15] nt
	s_add_u32 s12, s12, 0x2000
	s_addc_u32 s13, s13, 0
	s_add_u32 s14, s14, 0x1000
	s_addc_u32 s15, s15, 0
	global_load_dwordx2 v[42:43], v2, s[12:13] nt
	global_load_dword v69, v3, s[14:15] nt
	s_add_u32 s12, s12, 0x2000
	s_addc_u32 s13, s13, 0
	s_add_u32 s14, s14, 0x1000
	s_addc_u32 s15, s15, 0
	global_load_dwordx2 v[44:45], v2, s[12:13] nt
	global_load_dword v70, v3, s[14:15] nt
	s_add_u32 s12, s12, 0x2000
	s_addc_u32 s13, s13, 0
	s_add_u32 s14, s14, 0x1000
	s_addc_u32 s15, s15, 0
	global_load_dwordx2 v[46:47], v2, s[12:13] nt
	global_load_dword v71, v3, s[14:15] nt
	s_add_u32 s12, s12, 0x2000
	s_addc_u32 s13, s13, 0
	s_add_u32 s14, s14, 0x1000
	s_addc_u32 s15, s15, 0
	global_load_dwordx2 v[48:49], v2, s[12:13] nt
	global_load_dword v72, v3, s[14:15] nt
	s_add_u32 s12, s12, 0x2000
	s_addc_u32 s13, s13, 0
	s_add_u32 s14, s14, 0x1000
	s_addc_u32 s15, s15, 0
	global_load_dwordx2 v[50:51], v2, s[12:13] nt
	global_load_dword v73, v3, s[14:15] nt
	s_add_u32 s12, s12, 0x2000
	s_addc_u32 s13, s13, 0
	s_add_u32 s14, s14, 0x1000
	s_addc_u32 s15, s15, 0
	global_load_dwordx2 v[52:53], v2, s[12:13] nt
	global_load_dword v74, v3, s[14:15] nt
	s_add_u32 s12, s12, 0x2000
	s_addc_u32 s13, s13, 0
	s_add_u32 s14, s14, 0x1000
	s_addc_u32 s15, s15, 0
	global_load_dwordx2 v[54:55], v2, s[12:13] nt
	global_load_dword v75, v3, s[14:15] nt
	s_add_u32 s12, s12, 0x2000
	s_addc_u32 s13, s13, 0
	s_add_u32 s14, s14, 0x1000
	s_addc_u32 s15, s15, 0
	global_load_dwordx2 v[56:57], v2, s[12:13] nt
	global_load_dword v76, v3, s[14:15] nt
	s_add_u32 s12, s12, 0x2000
	s_addc_u32 s13, s13, 0
	s_add_u32 s14, s14, 0x1000
	s_addc_u32 s15, s15, 0
	global_load_dwordx2 v[58:59], v2, s[12:13] nt
	global_load_dword v77, v3, s[14:15] nt
	s_add_u32 s12, s12, 0x2000
	s_addc_u32 s13, s13, 0
	s_add_u32 s14, s14, 0x1000
	s_addc_u32 s15, s15, 0
	global_load_dwordx2 v[60:61], v2, s[12:13] nt
	global_load_dword v78, v3, s[14:15] nt
	s_add_u32 s12, s12, 0x2000
	s_addc_u32 s13, s13, 0
	s_add_u32 s14, s14, 0x1000
	s_addc_u32 s15, s15, 0
	global_load_dwordx2 v[62:63], v2, s[12:13] nt
	global_load_dword v79, v3, s[14:15] nt
	s_add_u32 s12, s12, 0x2000
	s_addc_u32 s13, s13, 0
	s_add_u32 s14, s14, 0x1000
	s_addc_u32 s15, s15, 0
	s_waitcnt vmcnt(62)
	v_pk_fma_f32 v[4:5], v[4:5], v[100:101], v[102:103]
	s_sub_u32 s10, s10, 1
	s_cmp_eq_u32 s10, 0
	s_cbranch_scc1 .Lp2d_prefix_done
; __device__ __forceinline__ float bf_lo(unsigned w) { return __uint_as_float(w << 16); }
; __device__ __forceinline__ float bf_hi(unsigned w) { return __uint_as_float(w & 0xffff0000u); }
; __global__ void __launch_bounds__(NTHR, 2) hybrid_block_fwd(Args a) {
;     ...
; #pragma unroll 4
;         for (int j = 0; j < chunk; ++j) { const f32x2 P = ((const f32x2*)(AGGP + (size_t)(b * NCH + j) * LW))[c2], Hj = ((const f32x2*)(AGGH + (size_t)(b * NCH + j) * LW))[c2]; H = P * H + Hj; }
;         const size_t r0 = (size_t)b * SEQ + (size_t)chunk * CH_L;
;         const u32x2* pab = (const u32x2*)((const unsigned*)AF + r0 * LW) + c2;
;         const unsigned* pg = (const unsigned*)(GELU_U + r0 * LW) + c2; unsigned* po = (unsigned*)(YCAT + r0 * KC + PW) + c2;
; #pragma unroll 16
;         for (int i = 0; i < CH_L; ++i) {
;             const u32x2 q = pab[(size_t)i * (LW / 2)]; const f32x2 av = (f32x2){__builtin_amdgcn_exp2f(bf_lo(q.x)), __builtin_amdgcn_exp2f(bf_lo(q.y))}, bv = (f32x2){bf_hi(q.x), bf_hi(q.y)}; const unsigned gq = pg[(size_t)i * (LW / 2)];
	s_waitcnt vmcnt(60)
	v_pk_fma_f32 v[4:5], v[4:5], v[104:105], v[106:107]
	s_sub_u32 s10, s10, 1
	s_cmp_eq_u32 s10, 0
	s_cbranch_scc1 .Lp2d_prefix_done
	s_waitcnt vmcnt(58)
	v_pk_fma_f32 v[4:5], v[4:5], v[108:109], v[110:111]
	s_sub_u32 s10, s10, 1
	s_cmp_eq_u32 s10, 0
	s_cbranch_scc1 .Lp2d_prefix_done
	s_waitcnt vmcnt(56)
	v_pk_fma_f32 v[4:5], v[4:5], v[112:113], v[114:115]
	s_sub_u32 s10, s10, 1
	s_cmp_eq_u32 s10, 0
	s_cbranch_scc1 .Lp2d_prefix_done
	s_waitcnt vmcnt(54)
	v_pk_fma_f32 v[4:5], v[4:5], v[116:117], v[118:119]
	s_sub_u32 s10, s10, 1
	s_cmp_eq_u32 s10, 0
	s_cbranch_scc1 .Lp2d_prefix_done
	s_waitcnt vmcnt(52)
	v_pk_fma_f32 v[4:5], v[4:5], v[120:121], v[122:123]
	s_sub_u32 s10, s10, 1
	s_cmp_eq_u32 s10, 0
	s_cbranch_scc1 .Lp2d_prefix_done
	s_waitcnt vmcnt(50)
	v_pk_fma_f32 v[4:5], v[4:5], v[124:125], v[126:127]
	s_sub_u32 s10, s10, 1
	s_cmp_eq_u32 s10, 0
	s_cbranch_scc1 .Lp2d_prefix_done
	s_waitcnt vmcnt(48)
	v_pk_fma_f32 v[4:5], v[4:5], v[128:129], v[130:131]
	s_sub_u32 s10, s10, 1
	s_cmp_eq_u32 s10, 0
	s_cbranch_scc1 .Lp2d_prefix_done
	s_waitcnt vmcnt(46)
	v_pk_fma_f32 v[4:5], v[4:5], v[132:133], v[134:135]
	s_sub_u32 s10, s10, 1
	s_cmp_eq_u32 s10, 0
	s_cbranch_scc1 .Lp2d_prefix_done
	s_waitcnt vmcnt(44)
	v_pk_fma_f32 v[4:5], v[4:5], v[136:137], v[138:139]
	s_sub_u32 s10, s10, 1
	s_cmp_eq_u32 s10, 0
	s_cbranch_scc1 .Lp2d_prefix_done
	s_waitcnt vmcnt(42)
	v_pk_fma_f32 v[4:5], v[4:5], v[140:141], v[142:143]
	s_sub_u32 s10, s10, 1
	s_cmp_eq_u32 s10, 0
	s_cbranch_scc1 .Lp2d_prefix_done
	s_waitcnt vmcnt(40)
	v_pk_fma_f32 v[4:5], v[4:5], v[144:145], v[146:147]
	s_sub_u32 s10, s10, 1
	s_cmp_eq_u32 s10, 0
	s_cbranch_scc1 .Lp2d_prefix_done
	s_waitcnt vmcnt(38)
	v_pk_fma_f32 v[4:5], v[4:5], v[148:149], v[150:151]
	s_sub_u32 s10, s10, 1
	s_cmp_eq_u32 s10, 0
	s_cbranch_scc1 .Lp2d_prefix_done
	s_waitcnt vmcnt(36)
	v_pk_fma_f32 v[4:5], v[4:5], v[152:153], v[154:155]
	s_sub_u32 s10, s10, 1
	s_cmp_eq_u32 s10, 0
	s_cbranch_scc1 .Lp2d_prefix_done
	s_waitcnt vmcnt(34)
	v_pk_fma_f32 v[4:5], v[4:5], v[156:157], v[158:159]
	s_sub_u32 s10, s10, 1
	s_cmp_eq_u32 s10, 0
	s_cbranch_scc1 .Lp2d_prefix_done
	s_waitcnt vmcnt(32)
	v_pk_fma_f32 v[4:5], v[4:5], v[160:161], v[162:163]
	s_sub_u32 s10, s10, 1
	s_cmp_eq_u32 s10, 0
	s_cbranch_scc1 .Lp2d_prefix_done
	s_branch .Lp2d_prefix_batch
.Lp2d_main_only:
	global_load_dwordx2 v[32:33], v2, s[12:13] nt
	global_load_dword v64, v3, s[14:15] nt
	s_add_u32 s12, s12, 0x2000
	s_addc_u32 s13, s13, 0
	s_add_u32 s14, s14, 0x1000
	s_addc_u32 s15, s15, 0
	global_load_dwordx2 v[34:35], v2, s[12:13] nt
	global_load_dword v65, v3, s[14:15] nt
	s_add_u32 s12, s12, 0x2000
	s_addc_u32 s13, s13, 0
	s_add_u32 s14, s14, 0x1000
	s_addc_u32 s15, s15, 0
	global_load_dwordx2 v[36:37], v2, s[12:13] nt
	global_load_dword v66, v3, s[14:15] nt
	s_add_u32 s12, s12, 0x2000
	s_addc_u32 s13, s13, 0
	s_add_u32 s14, s14, 0x1000
	s_addc_u32 s15, s15, 0
	global_load_dwordx2 v[38:39], v2, s[12:13] nt
	global_load_dword v67, v3, s[14:15] nt
	s_add_u32 s12, s12, 0x2000
	s_addc_u32 s13, s13, 0
	s_add_u32 s14, s14, 0x1000
	s_addc_u32 s15, s15, 0
	global_load_dwordx2 v[40:41], v2, s[12:13] nt
	global_load_dword v68, v3, s[14:15] nt
	s_add_u32 s12, s12, 0x2000
	s_addc_u32 s13, s13, 0
	s_add_u32 s14, s14, 0x1000
	s_addc_u32 s15, s15, 0
	global_load_dwordx2 v[42:43], v2, s[12:13] nt
	global_load_dword v69, v3, s[14:15] nt
	s_add_u32 s12, s12, 0x2000
	s_addc_u32 s13, s13, 0
	s_add_u32 s14, s14, 0x1000
	s_addc_u32 s15, s15, 0
	global_load_dwordx2 v[44:45], v2, s[12:13] nt
	global_load_dword v70, v3, s[14:15] nt
	s_add_u32 s12, s12, 0x2000
	s_addc_u32 s13, s13, 0
	s_add_u32 s14, s14, 0x1000
	s_addc_u32 s15, s15, 0
	global_load_dwordx2 v[46:47], v2, s[12:13] nt
	global_load_dword v71, v3, s[14:15] nt
	s_add_u32 s12, s12, 0x2000
	s_addc_u32 s13, s13, 0
	s_add_u32 s14, s14, 0x1000
	s_addc_u32 s15, s15, 0
	global_load_dwordx2 v[48:49], v2, s[12:13] nt
	global_load_dword v72, v3, s[14:15] nt
	s_add_u32 s12, s12, 0x2000
	s_addc_u32 s13, s13, 0
	s_add_u32 s14, s14, 0x1000
	s_addc_u32 s15, s15, 0
	global_load_dwordx2 v[50:51], v2, s[12:13] nt
	global_load_dword v73, v3, s[14:15] nt
	s_add_u32 s12, s12, 0x2000
	s_addc_u32 s13, s13, 0
	s_add_u32 s14, s14, 0x1000
	s_addc_u32 s15, s15, 0
	global_load_dwordx2 v[52:53], v2, s[12:13] nt
	global_load_dword v74, v3, s[14:15] nt
	s_add_u32 s12, s12, 0x2000
	s_addc_u32 s13, s13, 0
	s_add_u32 s14, s14, 0x1000
	s_addc_u32 s15, s15, 0
	global_load_dwordx2 v[54:55], v2, s[12:13] nt
	global_load_dword v75, v3, s[14:15] nt
	s_add_u32 s12, s12, 0x2000
	s_addc_u32 s13, s13, 0
	s_add_u32 s14, s14, 0x1000
	s_addc_u32 s15, s15, 0
	global_load_dwordx2 v[56:57], v2, s[12:13] nt
	global_load_dword v76, v3, s[14:15] nt
	s_add_u32 s12, s12, 0x2000
	s_addc_u32 s13, s13, 0
	s_add_u32 s14, s14, 0x1000
	s_addc_u32 s15, s15, 0
	global_load_dwordx2 v[58:59], v2, s[12:13] nt
	global_load_dword v77, v3, s[14:15] nt
	s_add_u32 s12, s12, 0x2000
	s_addc_u32 s13, s13, 0
	s_add_u32 s14, s14, 0x1000
	s_addc_u32 s15, s15, 0
	global_load_dwordx2 v[60:61], v2, s[12:13] nt
	global_load_dword v78, v3, s[14:15] nt
	s_add_u32 s12, s12, 0x2000
	s_addc_u32 s13, s13, 0
	s_add_u32 s14, s14, 0x1000
	s_addc_u32 s15, s15, 0
	global_load_dwordx2 v[62:63], v2, s[12:13] nt
	global_load_dword v79, v3, s[14:15] nt
	s_add_u32 s12, s12, 0x2000
	s_addc_u32 s13, s13, 0
	s_add_u32 s14, s14, 0x1000
	s_addc_u32 s15, s15, 0
	s_branch .Lp2d_prefix_done
